# attn-B M segment: first lgkmcnt wait moved behind the ALiBi MFMA that needs no LDS data (on top of v70)
# baseline (speedup 1.0000x reference)
.LBB0_698:
	s_add_i32 s12, s29, 0xffff8000
	s_add_i32 s16, s29, 0x4000
	s_and_b32 s13, s16, 0xc000
	s_and_b32 s12, s12, 0xc000
	v_add_u32_e32 v2, s12, v172
	ds_read_b128 v[186:189], v2 offset:0
	ds_read_b128 v[190:193], v2 offset:0x2000
	v_add_u32_e32 v2, s12, v173
	ds_read_b128 v[194:197], v2 offset:0
	ds_read_b128 v[198:201], v2 offset:0x2000
	v_add_u32_e32 v2, s12, v184
	ds_read_b128 v[202:205], v2 offset:0
	ds_read_b128 v[206:209], v2 offset:0x2000
	v_add_u32_e32 v2, s12, v185
	ds_read_b128 v[210:213], v2 offset:0
	ds_read_b128 v[214:217], v2 offset:0x2000
	v_add_u32_e32 v149, s13, v171
	ds_read_b64_tr_b16 v[218:219], v149 offset:0
	ds_read_b64_tr_b16 v[220:221], v149 offset:0x800
	ds_read_b64_tr_b16 v[222:223], v149 offset:0x1000
	ds_read_b64_tr_b16 v[224:225], v149 offset:0x1800
	ds_read_b64_tr_b16 v[226:227], v149 offset:0x2000
	ds_read_b64_tr_b16 v[228:229], v149 offset:0x2800
	ds_read_b64_tr_b16 v[242:243], v149 offset:0x3000
	ds_read_b64_tr_b16 v[244:245], v149 offset:0x3800
	s_cmp_gt_i32 s27, s19
	s_cselect_b64 vcc, -1, 0
	s_and_b64 s[12:13], vcc, exec
	s_cselect_b32 s12, 0x8000, 0
	v_xor_b32_e32 v2, s12, v164
	v_mov_b32_e32 v4, v3
	v_mov_b32_e32 v5, v3

	s_nop 1
	v_mfma_f32_32x32x16_bf16 v[70:85], v[118:121], v[2:5], 0
	s_waitcnt lgkmcnt(8)
	v_mfma_f32_32x32x16_bf16 v[86:101], v[186:189], v[102:105], v[70:85]
	v_mfma_f32_32x32x16_bf16 v[70:85], v[190:193], v[102:105], v[70:85]
	v_mfma_f32_32x32x16_bf16 v[86:101], v[194:197], v[106:109], v[86:101]
	v_mfma_f32_32x32x16_bf16 v[70:85], v[198:201], v[106:109], v[70:85]
	v_mfma_f32_32x32x16_bf16 v[86:101], v[202:205], v[110:113], v[86:101]
	v_mfma_f32_32x32x16_bf16 v[70:85], v[206:209], v[110:113], v[70:85]
	v_mfma_f32_32x32x16_bf16 v[86:101], v[210:213], v[114:117], v[86:101]
	v_mfma_f32_32x32x16_bf16 v[70:85], v[214:217], v[114:117], v[70:85]
	ds_read_b64_tr_b16 v[186:187], v149 offset:0x200
	ds_read_b64_tr_b16 v[188:189], v149 offset:0xa00
	ds_read_b64_tr_b16 v[190:191], v149 offset:0x1200
	ds_read_b64_tr_b16 v[192:193], v149 offset:0x1a00
	ds_read_b64_tr_b16 v[194:195], v149 offset:0x2200
	ds_read_b64_tr_b16 v[196:197], v149 offset:0x2a00
	ds_read_b64_tr_b16 v[198:199], v149 offset:0x3200
	ds_read_b64_tr_b16 v[200:201], v149 offset:0x3a00
	s_waitcnt lgkmcnt(8)
	v_mfma_f32_32x32x16_bf16 v[54:69], v[134:137], v[218:221], v[54:69]
	v_mfma_f32_32x32x16_bf16 v[54:69], v[130:133], v[222:225], v[54:69]
	v_mfma_f32_32x32x16_bf16 v[54:69], v[126:129], v[226:229], v[54:69]
	v_mfma_f32_32x32x16_bf16 v[54:69], v[122:125], v[242:245], v[54:69]
	ds_read_b64_tr_b16 v[202:203], v149 offset:0x400
	ds_read_b64_tr_b16 v[204:205], v149 offset:0xc00
	ds_read_b64_tr_b16 v[206:207], v149 offset:0x1400
	ds_read_b64_tr_b16 v[208:209], v149 offset:0x1c00
	ds_read_b64_tr_b16 v[210:211], v149 offset:0x2400
	ds_read_b64_tr_b16 v[212:213], v149 offset:0x2c00
	ds_read_b64_tr_b16 v[214:215], v149 offset:0x3400
	ds_read_b64_tr_b16 v[216:217], v149 offset:0x3c00
	s_waitcnt lgkmcnt(8)
	v_mfma_f32_32x32x16_bf16 v[38:53], v[134:137], v[186:189], v[38:53]
	v_mfma_f32_32x32x16_bf16 v[38:53], v[130:133], v[190:193], v[38:53]
	v_mfma_f32_32x32x16_bf16 v[38:53], v[126:129], v[194:197], v[38:53]
	v_mfma_f32_32x32x16_bf16 v[38:53], v[122:125], v[198:201], v[38:53]
	ds_read_b64_tr_b16 v[186:187], v149 offset:0x600
	ds_read_b64_tr_b16 v[188:189], v149 offset:0xe00
	ds_read_b64_tr_b16 v[190:191], v149 offset:0x1600
	ds_read_b64_tr_b16 v[192:193], v149 offset:0x1e00
	ds_read_b64_tr_b16 v[194:195], v149 offset:0x2600
	ds_read_b64_tr_b16 v[196:197], v149 offset:0x2e00
	ds_read_b64_tr_b16 v[198:199], v149 offset:0x3600
	ds_read_b64_tr_b16 v[200:201], v149 offset:0x3e00
	s_waitcnt lgkmcnt(8)
	v_mfma_f32_32x32x16_bf16 v[22:37], v[134:137], v[202:205], v[22:37]
	v_mfma_f32_32x32x16_bf16 v[22:37], v[130:133], v[206:209], v[22:37]
	v_mfma_f32_32x32x16_bf16 v[22:37], v[126:129], v[210:213], v[22:37]
	v_mfma_f32_32x32x16_bf16 v[22:37], v[122:125], v[214:217], v[22:37]
	s_waitcnt lgkmcnt(0)
	v_mfma_f32_32x32x16_bf16 v[6:21], v[134:137], v[186:189], v[6:21]
	v_mfma_f32_32x32x16_bf16 v[6:21], v[130:133], v[190:193], v[6:21]
	v_mfma_f32_32x32x16_bf16 v[6:21], v[126:129], v[194:197], v[6:21]
	v_mfma_f32_32x32x16_bf16 v[6:21], v[122:125], v[198:201], v[6:21]
	s_waitcnt lgkmcnt(0)
	s_barrier
	s_add_i32 s12, s28, 0xffffff80
	v_cvt_f32_u32_e32 v2, s12
	s_cmp_lg_u32 s19, s27
	v_sub_f32_e32 v4, v163, v2
	s_cbranch_scc0 .Lb_diag
